# GQA main loop: K-prefetch address product on the scalar unit (s_mul_i32 + 64-bit VALU add instead of v_mad_i64_i32), remaining s_nop stalls in front of the permlane/second DMA filled or removed
# speedup vs baseline: 1.0023x; 1.0006x over previous
.LBB0_707:
	s_add_i32 s22, s23, 2
	v_add_u32_e32 v186, s0, v207
	ds_read_b64_tr_b16 v[178:179], v186 offset:24576
	ds_read_b64_tr_b16 v[180:181], v186 offset:25088
	s_waitcnt lgkmcnt(9)
	v_mfma_f32_32x32x16_bf16 v[98:113], v[174:177], v[142:145], v[34:49]
	v_add_f32_e32 v82, v66, v67
	v_add_f32_e32 v82, v68, v82
	v_add_f32_e32 v82, v69, v82
	v_add_f32_e32 v82, v70, v82
	v_add_f32_e32 v82, v71, v82
	v_cvt_pk_bf16_f32 v134, v66, v67
	v_cvt_pk_bf16_f32 v135, v68, v69
	ds_read_b64_tr_b16 v[174:175], v186 offset:28672
	ds_read_b64_tr_b16 v[176:177], v186 offset:29184
	v_add_f32_e32 v66, v72, v82
	s_waitcnt lgkmcnt(10)
	v_mfma_f32_32x32x16_bf16 v[82:97], v[170:173], v[142:145], v[34:49]
	v_add_f32_e32 v66, v73, v66
	v_add_f32_e32 v66, v74, v66
	v_add_f32_e32 v114, v75, v66
	v_cvt_pk_bf16_f32 v136, v70, v71
	v_cvt_pk_bf16_f32 v137, v72, v73
	ds_read_b64_tr_b16 v[66:67], v186 offset:25600
	ds_read_b64_tr_b16 v[68:69], v186 offset:26112
	s_waitcnt lgkmcnt(11)
	v_mfma_f32_32x32x16_bf16 v[98:113], v[166:169], v[138:141], v[98:113]
	v_add_f32_e32 v70, v76, v114
	v_add_f32_e32 v70, v77, v70
	v_add_f32_e32 v70, v78, v70
	v_add_f32_e32 v114, v79, v70
	v_cvt_pk_bf16_f32 v126, v74, v75
	v_cvt_pk_bf16_f32 v127, v76, v77
	ds_read_b64_tr_b16 v[70:71], v186 offset:29696
	ds_read_b64_tr_b16 v[72:73], v186 offset:30208
	s_waitcnt lgkmcnt(12)
	v_mfma_f32_32x32x16_bf16 v[82:97], v[162:165], v[138:141], v[82:97]
	v_add_f32_e32 v74, v80, v114
	v_add_f32_e32 v74, v81, v74
	v_add_f32_e32 v74, v50, v74
	v_add_f32_e32 v114, v51, v74
	v_cvt_pk_bf16_f32 v128, v78, v79
	v_cvt_pk_bf16_f32 v129, v80, v81
	ds_read_b64_tr_b16 v[74:75], v186 offset:26624
	ds_read_b64_tr_b16 v[76:77], v186 offset:27136
	s_waitcnt lgkmcnt(13)
	v_mfma_f32_32x32x16_bf16 v[98:113], v[158:161], v[130:133], v[98:113]
	v_add_f32_e32 v78, v52, v114
	v_add_f32_e32 v78, v53, v78
	v_add_f32_e32 v78, v54, v78
	v_add_f32_e32 v78, v55, v78
	v_cvt_pk_bf16_f32 v118, v50, v51
	v_cvt_pk_bf16_f32 v119, v52, v53
	ds_read_b64_tr_b16 v[50:51], v186 offset:30720
	ds_read_b64_tr_b16 v[52:53], v186 offset:31232
	s_waitcnt lgkmcnt(14)
	v_mfma_f32_32x32x16_bf16 v[82:97], v[154:157], v[130:133], v[82:97]
	v_add_f32_e32 v78, v56, v78
	v_add_f32_e32 v78, v57, v78
	v_add_f32_e32 v78, v58, v78
	v_add_f32_e32 v78, v59, v78
	v_cvt_pk_bf16_f32 v120, v54, v55
	v_cvt_pk_bf16_f32 v121, v56, v57
	ds_read_b64_tr_b16 v[54:55], v186 offset:27648
	ds_read_b64_tr_b16 v[56:57], v186 offset:28160
	s_waitcnt lgkmcnt(14)
	v_mfma_f32_32x32x16_bf16 v[98:113], v[150:153], v[122:125], v[98:113]
	v_add_f32_e32 v78, v60, v78
	v_add_f32_e32 v78, v61, v78
	v_add_f32_e32 v78, v62, v78
	v_add_f32_e32 v78, v63, v78
	v_cvt_pk_bf16_f32 v114, v58, v59
	v_cvt_pk_bf16_f32 v115, v60, v61
	ds_read_b64_tr_b16 v[58:59], v186 offset:31744
	ds_read_b64_tr_b16 v[60:61], v186 offset:32256
	v_mfma_f32_32x32x16_bf16 v[82:97], v[146:149], v[122:125], v[82:97]
	v_add_f32_e32 v78, v64, v78
	v_add_f32_e32 v78, v65, v78
	v_cvt_pk_bf16_f32 v116, v62, v63
	v_cvt_pk_bf16_f32 v117, v64, v65
	s_cmpk_gt_u32 s22, 0x7c
	s_cselect_b64 s[0:1], -1, 0
	s_cmpk_lt_u32 s22, 0x7d
	s_cselect_b32 s4, 0, 0xffffff80
	s_cselect_b32 s5, s9, s20
	s_add_i32 s4, s4, s23
	s_lshl_b32 s4, s4, 6
	s_add_i32 s4, s4, s5
	s_addk_i32 s4, 0x140
	s_mul_i32 s4, s4, 0xe00
	s_mov_b32 s5, 0
	s_add_i32 m0, s24, s18
	v_lshl_add_u64 v[62:63], v[192:193], 0, s[4:5]
	global_load_lds_dwordx4 v[62:63], off
	v_max_f32_e32 v62, v98, v99
	v_max3_f32 v63, v100, v101, v83
	v_max3_f32 v62, v62, v82, v84
	v_max3_f32 v62, v62, v85, v102
	v_max3_f32 v63, v63, v104, v105
	v_max3_f32 v62, v62, v103, v86
	v_max3_f32 v63, v63, v88, v89
	v_max3_f32 v62, v62, v87, v106
	v_max3_f32 v63, v63, v108, v109
	v_max3_f32 v62, v62, v107, v90
	v_max3_f32 v63, v63, v92, v93
	v_max3_f32 v62, v62, v91, v110
	v_max3_f32 v63, v63, v112, v113
	v_max3_f32 v62, v62, v111, v94
	v_max3_f32 v63, v63, v96, v97
	v_max3_f32 v62, v62, v95, v63
	v_mov_b32_e32 v63, v62
	s_add_i32 m0, s21, s19
	v_add_f32_e32 v224, v224, v78
	v_permlane32_swap_b32_e32 v62, v63
	global_load_lds_dwordx4 v[196:197], off
	v_max_f32_e32 v62, v62, v63
	v_cmp_lt_f32_e32 vcc, s51, v62
	s_cmp_lg_u64 vcc, 0
	s_cselect_b64 s[4:5], -1, 0
	s_cbranch_vccnz .LBB0_715

.LBB0_710:
	s_add_i32 s4, s21, 0x2000
	s_cmpk_lg_i32 s21, 0x4000
	s_cselect_b32 s25, s4, 0
	v_add_u32_e32 v186, s24, v207
	ds_read_b64_tr_b16 v[150:151], v186 offset:24576
	ds_read_b64_tr_b16 v[152:153], v186 offset:25088
	s_waitcnt lgkmcnt(9)
	v_mfma_f32_32x32x16_bf16 v[66:81], v[62:65], v[142:145], v[34:49]
	v_add_f32_e32 v50, v98, v99
	v_add_f32_e32 v50, v100, v50
	v_add_f32_e32 v50, v101, v50
	v_add_f32_e32 v50, v102, v50
	v_add_f32_e32 v50, v103, v50
	v_cvt_pk_bf16_f32 v134, v98, v99
	v_cvt_pk_bf16_f32 v135, v100, v101
	ds_read_b64_tr_b16 v[146:147], v186 offset:28672
	ds_read_b64_tr_b16 v[148:149], v186 offset:29184
	v_add_f32_e32 v50, v104, v50
	v_add_f32_e32 v50, v105, v50
	v_add_f32_e32 v50, v106, v50
	v_add_f32_e32 v114, v107, v50
	s_waitcnt lgkmcnt(10)
	v_mfma_f32_32x32x16_bf16 v[50:65], v[174:177], v[142:145], v[34:49]
	v_cvt_pk_bf16_f32 v136, v102, v103
	v_cvt_pk_bf16_f32 v137, v104, v105
	ds_read_b64_tr_b16 v[98:99], v186 offset:25600
	ds_read_b64_tr_b16 v[100:101], v186 offset:26112
	s_waitcnt lgkmcnt(11)
	v_mfma_f32_32x32x16_bf16 v[66:81], v[178:181], v[138:141], v[66:81]
	v_add_f32_e32 v102, v108, v114
	v_add_f32_e32 v102, v109, v102
	v_add_f32_e32 v102, v110, v102
	v_add_f32_e32 v114, v111, v102
	v_cvt_pk_bf16_f32 v126, v106, v107
	v_cvt_pk_bf16_f32 v127, v108, v109
	ds_read_b64_tr_b16 v[102:103], v186 offset:29696
	ds_read_b64_tr_b16 v[104:105], v186 offset:30208
	s_waitcnt lgkmcnt(12)
	v_mfma_f32_32x32x16_bf16 v[50:65], v[170:173], v[138:141], v[50:65]
	v_add_f32_e32 v106, v112, v114
	v_add_f32_e32 v106, v113, v106
	v_add_f32_e32 v106, v82, v106
	v_add_f32_e32 v114, v83, v106
	v_cvt_pk_bf16_f32 v128, v110, v111
	v_cvt_pk_bf16_f32 v129, v112, v113
	ds_read_b64_tr_b16 v[106:107], v186 offset:26624
	ds_read_b64_tr_b16 v[108:109], v186 offset:27136
	s_waitcnt lgkmcnt(13)
	v_mfma_f32_32x32x16_bf16 v[66:81], v[166:169], v[130:133], v[66:81]
	v_add_f32_e32 v110, v84, v114
	v_add_f32_e32 v110, v85, v110
	v_add_f32_e32 v110, v86, v110
	v_add_f32_e32 v110, v87, v110
	v_cvt_pk_bf16_f32 v118, v82, v83
	v_cvt_pk_bf16_f32 v119, v84, v85
	ds_read_b64_tr_b16 v[82:83], v186 offset:30720
	ds_read_b64_tr_b16 v[84:85], v186 offset:31232
	s_waitcnt lgkmcnt(14)
	v_mfma_f32_32x32x16_bf16 v[50:65], v[162:165], v[130:133], v[50:65]
	v_add_f32_e32 v110, v88, v110
	v_add_f32_e32 v110, v89, v110
	v_add_f32_e32 v110, v90, v110
	v_add_f32_e32 v110, v91, v110
	v_cvt_pk_bf16_f32 v120, v86, v87
	v_cvt_pk_bf16_f32 v121, v88, v89
	ds_read_b64_tr_b16 v[86:87], v186 offset:27648
	ds_read_b64_tr_b16 v[88:89], v186 offset:28160
	s_waitcnt lgkmcnt(14)
	v_mfma_f32_32x32x16_bf16 v[66:81], v[158:161], v[122:125], v[66:81]
	v_add_f32_e32 v110, v92, v110
	v_add_f32_e32 v110, v93, v110
	v_add_f32_e32 v110, v94, v110
	v_add_f32_e32 v110, v95, v110
	v_cvt_pk_bf16_f32 v114, v90, v91
	v_cvt_pk_bf16_f32 v115, v92, v93
	ds_read_b64_tr_b16 v[90:91], v186 offset:31744
	ds_read_b64_tr_b16 v[92:93], v186 offset:32256
	v_mfma_f32_32x32x16_bf16 v[50:65], v[154:157], v[122:125], v[50:65]
	v_add_f32_e32 v110, v96, v110
	v_add_f32_e32 v110, v97, v110
	v_cvt_pk_bf16_f32 v116, v94, v95
	v_cvt_pk_bf16_f32 v117, v96, v97
	s_cmpk_lt_u32 s22, 0x7c
	s_cselect_b32 s4, 0, 0xffffff80
	s_cselect_b32 s5, s9, s20
	s_add_i32 s4, s4, s23
	s_lshl_b32 s4, s4, 6
	s_add_i32 s4, s4, s5
	s_addk_i32 s4, 0x180
	s_mul_i32 s4, s4, 0xe00
	s_mov_b32 s5, 0
	s_add_i32 m0, s21, s18
	v_lshl_add_u64 v[94:95], v[192:193], 0, s[4:5]
	global_load_lds_dwordx4 v[94:95], off
	s_add_i32 m0, s25, s19
	v_lshl_add_u64 v[94:95], v[196:197], 0, s[30:31]
	global_load_lds_dwordx4 v[94:95], off
	v_max_f32_e32 v94, v66, v67
	v_max3_f32 v95, v68, v69, v51
	v_max3_f32 v94, v94, v50, v52
	v_max3_f32 v94, v94, v53, v70
	v_max3_f32 v95, v95, v72, v73
	v_max3_f32 v94, v94, v71, v54
	v_max3_f32 v95, v95, v56, v57
	v_max3_f32 v94, v94, v55, v74
	v_max3_f32 v95, v95, v76, v77
	v_max3_f32 v94, v94, v75, v58
	v_max3_f32 v95, v95, v60, v61
	v_max3_f32 v94, v94, v59, v78
	v_max3_f32 v95, v95, v80, v81
	v_max3_f32 v94, v94, v79, v62
	v_max3_f32 v95, v95, v64, v65
	v_max3_f32 v94, v94, v63, v95
	v_mov_b32_e32 v95, v94
	v_add_f32_e32 v224, v224, v110
	s_nop 0
	v_permlane32_swap_b32_e32 v94, v95
	v_max_f32_e32 v94, v94, v95
	v_cmp_lt_f32_e32 vcc, s51, v94
	s_cmp_lg_u64 vcc, 0
	s_cselect_b64 s[4:5], -1, 0
	s_cbranch_vccnz .LBB0_718
